# v61 + P5: SSP loads of 6 of the 8 row blocks issued one MMA block earlier (after the last K-tile's final barrier, into v228-251)
# baseline (speedup 1.0000x reference)
; #define PG8_STAGE(bufoff, gbase, voff) do { _Pragma("unroll") for (int _i = 0; _i < 2; ++_i) \
;         __builtin_amdgcn_global_load_lds((const unsigned*)((const char*)(gbase) + (voff)[_i]), (PG8_LAS unsigned*)(lds + (bufoff) + ldsw + _i * 8192), 16, 0, 0); } while (0)
; #define PG8_LDA(dst, b, h) do { _Pragma("unroll") for (int m = 0; m < 4; ++m) _Pragma("unroll") for (int k = 0; k < 2; ++k) dst[m][k] = *(const PG8_LAS bf16x8*)(lds + PG8_SA(b, h) + aoff + m * 2048 + k * 1024); } while (0)
; #define PG8_LDB(dst, b, h) do { _Pragma("unroll") for (int n = 0; n < 2; ++n) _Pragma("unroll") for (int k = 0; k < 2; ++k) dst[n][k] = *(const PG8_LAS bf16x8*)(lds + PG8_SB(b, h) + boff + n * 2048 + k * 1024); } while (0)
; #define PG8_MMA(ai, bj, At, Bt) do { __builtin_amdgcn_s_setprio(1); _Pragma("unroll") for (int m = 0; m < 4; ++m) _Pragma("unroll") for (int n = 0; n < 2; ++n) _Pragma("unroll") for (int k = 0; k < 2; ++k) \
;         acc[ai][bj][m][n] = __builtin_amdgcn_mfma_f32_16x16x32_bf16(Bt[n][k], At[m][k], acc[ai][bj][m][n], 0, 0, 0); __builtin_amdgcn_s_setprio(0); } while (0)
; #define PG8_WAIT_V(n) asm volatile("s_waitcnt vmcnt(" #n ")" ::: "memory")
; #define PG8_WAIT_L(n) asm volatile("s_waitcnt lgkmcnt(" #n ")" ::: "memory")
; #define PG8_BAR __builtin_amdgcn_s_barrier()
; #define PG8_SCHED __builtin_amdgcn_sched_barrier(0)
; template <class Epi, class Sched, bool ALIGN_EPI = false, bool SP2 = false>
; __device__ __forceinline__ void gemm_phase(PG8_LAS unsigned char* lds, const Gemm g, const Sched& S, const Epi& E) {
;     ...
;             PG8_WAIT_V(8); PG8_WAIT_L(0); PG8_BAR; PG8_MMA(0, 0, At, B0); PG8_MMA(0, 1, At, B1); PG8_BAR; PG8_SCHED;
;             PG8_LDA(At, 0, 1); PG8_STAGE(PG8_SB(0, 0), b2, voffB); PG8_STAGE(PG8_SB(0, 1), b2 + hstep, voffB); PG8_STAGE(PG8_SA(0, 0), a2, voffA);
;             PG8_WAIT_V(8); PG8_WAIT_L(0); PG8_BAR; PG8_MMA(1, 0, At, B0); PG8_MMA(1, 1, At, B1); PG8_BAR; PG8_SCHED;
;             PG8_LDB(B0, 1, 0); PG8_LDB(B1, 1, 1); PG8_SCHED; PG8_LDA(At, 1, 0); PG8_STAGE(PG8_SA(0, 1), a2 + hstep, voffA);
;             PG8_WAIT_V(8); PG8_WAIT_L(0); PG8_BAR; PG8_MMA(0, 0, At, B0); PG8_MMA(0, 1, At, B1); PG8_BAR; PG8_SCHED;
.Lrj_P5_1:
	s_waitcnt lgkmcnt(0)
	s_barrier
	s_setprio 1
	s_waitcnt lgkmcnt(0)
	v_mfma_f32_16x16x32_bf16 v[60:63], v[144:147], v[184:187], v[60:63]
	v_mfma_f32_16x16x32_bf16 v[56:59], v[160:163], v[184:187], v[56:59]
	v_mfma_f32_16x16x32_bf16 v[44:47], v[144:147], v[192:195], v[44:47]
	v_mfma_f32_16x16x32_bf16 v[40:43], v[160:163], v[192:195], v[40:43]
	v_mfma_f32_16x16x32_bf16 v[28:31], v[144:147], v[200:203], v[28:31]
	v_mfma_f32_16x16x32_bf16 v[24:27], v[160:163], v[200:203], v[24:27]
	v_mfma_f32_16x16x32_bf16 v[12:15], v[144:147], v[208:211], v[12:15]
	v_mfma_f32_16x16x32_bf16 v[8:11], v[160:163], v[208:211], v[8:11]
	v_mfma_f32_16x16x32_bf16 v[60:63], v[156:159], v[188:191], v[60:63]
	v_mfma_f32_16x16x32_bf16 v[56:59], v[164:167], v[188:191], v[56:59]
	v_mfma_f32_16x16x32_bf16 v[44:47], v[156:159], v[196:199], v[44:47]
	v_mfma_f32_16x16x32_bf16 v[40:43], v[164:167], v[196:199], v[40:43]
	v_mfma_f32_16x16x32_bf16 v[28:31], v[156:159], v[204:207], v[28:31]
	v_mfma_f32_16x16x32_bf16 v[24:27], v[164:167], v[204:207], v[24:27]
	v_mfma_f32_16x16x32_bf16 v[12:15], v[156:159], v[212:215], v[12:15]
	v_mfma_f32_16x16x32_bf16 v[8:11], v[164:167], v[212:215], v[8:11]
	s_setprio 0
	s_setprio 1
	v_mfma_f32_16x16x32_bf16 v[52:55], v[168:171], v[184:187], v[52:55]
	v_mfma_f32_16x16x32_bf16 v[48:51], v[176:179], v[184:187], v[48:51]
	v_mfma_f32_16x16x32_bf16 v[36:39], v[168:171], v[192:195], v[36:39]
	v_mfma_f32_16x16x32_bf16 v[32:35], v[176:179], v[192:195], v[32:35]
	v_mfma_f32_16x16x32_bf16 v[20:23], v[168:171], v[200:203], v[20:23]
	v_mfma_f32_16x16x32_bf16 v[16:19], v[176:179], v[200:203], v[16:19]
	v_mfma_f32_16x16x32_bf16 v[4:7], v[168:171], v[208:211], v[4:7]
	v_mfma_f32_16x16x32_bf16 v[0:3], v[176:179], v[208:211], v[0:3]
	v_mfma_f32_16x16x32_bf16 v[52:55], v[172:175], v[188:191], v[52:55]
	v_mfma_f32_16x16x32_bf16 v[48:51], v[180:183], v[188:191], v[48:51]
	v_mfma_f32_16x16x32_bf16 v[36:39], v[172:175], v[196:199], v[36:39]
	v_mfma_f32_16x16x32_bf16 v[32:35], v[180:183], v[196:199], v[32:35]
	v_mfma_f32_16x16x32_bf16 v[20:23], v[172:175], v[204:207], v[20:23]
	v_mfma_f32_16x16x32_bf16 v[16:19], v[180:183], v[204:207], v[16:19]
	v_mfma_f32_16x16x32_bf16 v[4:7], v[172:175], v[212:215], v[4:7]
	v_mfma_f32_16x16x32_bf16 v[0:3], v[180:183], v[212:215], v[0:3]
	s_setprio 0
	s_barrier
	s_add_i32 s66, 0, 0x18000
	v_add_u32_e32 v155, s66, v149
	s_add_i32 s67, 0, 0x1c000
	ds_read_b128 v[144:147], v155
	ds_read_b128 v[156:159], v155 offset:1024
	ds_read_b128 v[160:163], v155 offset:2048
	ds_read_b128 v[164:167], v155 offset:3072
	v_add_u32_e32 v155, s67, v149
	ds_read_b128 v[168:171], v155
	ds_read_b128 v[172:175], v155 offset:1024
	ds_read_b128 v[176:179], v155 offset:2048
	ds_read_b128 v[180:183], v155 offset:3072
	s_add_u32 s36, s36, 0x40000
	s_addc_u32 s37, s37, 0
	s_mov_b32 m0, s43
	v_lshl_add_u64 v[224:225], s[36:37], 0, v[134:135]
	ds_read_b128 v[184:187], v153 offset:32768
	ds_read_b128 v[188:191], v153 offset:33792
	ds_read_b128 v[192:195], v153 offset:34816
	ds_read_b128 v[196:199], v153 offset:35840
	ds_read_b128 v[200:203], v153 offset:36864
	ds_read_b128 v[204:207], v153 offset:37888
	ds_read_b128 v[208:211], v153 offset:38912
	ds_read_b128 v[212:215], v153 offset:39936
	global_load_lds_dwordx4 v[224:225], off
	v_lshl_add_u64 v[224:225], s[36:37], 0, v[130:131]
	s_mov_b32 m0, s46
	s_nop 0
	global_load_lds_dwordx4 v[224:225], off
	s_waitcnt vmcnt(8)
	s_waitcnt lgkmcnt(0)
	s_barrier
	s_setprio 1
	s_waitcnt lgkmcnt(0)
	v_mfma_f32_16x16x32_bf16 v[124:127], v[144:147], v[184:187], v[124:127]
	v_mfma_f32_16x16x32_bf16 v[120:123], v[160:163], v[184:187], v[120:123]
	v_mfma_f32_16x16x32_bf16 v[108:111], v[144:147], v[192:195], v[108:111]
	v_mfma_f32_16x16x32_bf16 v[104:107], v[160:163], v[192:195], v[104:107]
	v_mfma_f32_16x16x32_bf16 v[92:95], v[144:147], v[200:203], v[92:95]
	v_mfma_f32_16x16x32_bf16 v[88:91], v[160:163], v[200:203], v[88:91]
	v_mfma_f32_16x16x32_bf16 v[76:79], v[144:147], v[208:211], v[76:79]
	v_mfma_f32_16x16x32_bf16 v[72:75], v[160:163], v[208:211], v[72:75]
	v_mfma_f32_16x16x32_bf16 v[124:127], v[156:159], v[188:191], v[124:127]
	v_mfma_f32_16x16x32_bf16 v[120:123], v[164:167], v[188:191], v[120:123]
	v_mfma_f32_16x16x32_bf16 v[108:111], v[156:159], v[196:199], v[108:111]
	v_mfma_f32_16x16x32_bf16 v[104:107], v[164:167], v[196:199], v[104:107]
	v_mfma_f32_16x16x32_bf16 v[92:95], v[156:159], v[204:207], v[92:95]
	v_mfma_f32_16x16x32_bf16 v[88:91], v[164:167], v[204:207], v[88:91]
	v_mfma_f32_16x16x32_bf16 v[76:79], v[156:159], v[212:215], v[76:79]
	v_mfma_f32_16x16x32_bf16 v[72:75], v[164:167], v[212:215], v[72:75]
	s_setprio 0
	s_setprio 1
	v_mfma_f32_16x16x32_bf16 v[116:119], v[168:171], v[184:187], v[116:119]
	v_mfma_f32_16x16x32_bf16 v[112:115], v[176:179], v[184:187], v[112:115]
	v_mfma_f32_16x16x32_bf16 v[100:103], v[168:171], v[192:195], v[100:103]
	v_mfma_f32_16x16x32_bf16 v[96:99], v[176:179], v[192:195], v[96:99]
	v_mfma_f32_16x16x32_bf16 v[84:87], v[168:171], v[200:203], v[84:87]
	v_mfma_f32_16x16x32_bf16 v[80:83], v[176:179], v[200:203], v[80:83]
	v_mfma_f32_16x16x32_bf16 v[68:71], v[168:171], v[208:211], v[68:71]
	v_mfma_f32_16x16x32_bf16 v[64:67], v[176:179], v[208:211], v[64:67]
	v_mfma_f32_16x16x32_bf16 v[116:119], v[172:175], v[188:191], v[116:119]
	v_mfma_f32_16x16x32_bf16 v[112:115], v[180:183], v[188:191], v[112:115]
	v_mfma_f32_16x16x32_bf16 v[100:103], v[172:175], v[196:199], v[100:103]
	v_mfma_f32_16x16x32_bf16 v[96:99], v[180:183], v[196:199], v[96:99]
	v_mfma_f32_16x16x32_bf16 v[84:87], v[172:175], v[204:207], v[84:87]
	v_mfma_f32_16x16x32_bf16 v[80:83], v[180:183], v[204:207], v[80:83]
	v_mfma_f32_16x16x32_bf16 v[68:71], v[172:175], v[212:215], v[68:71]
	v_mfma_f32_16x16x32_bf16 v[64:67], v[180:183], v[212:215], v[64:67]
	s_setprio 0
	s_barrier
; #define PG8_STAGE(bufoff, gbase, voff) do { _Pragma("unroll") for (int _i = 0; _i < 2; ++_i) \
;         __builtin_amdgcn_global_load_lds((const unsigned*)((const char*)(gbase) + (voff)[_i]), (PG8_LAS unsigned*)(lds + (bufoff) + ldsw + _i * 8192), 16, 0, 0); } while (0)
; #define PG8_LDA(dst, b, h) do { _Pragma("unroll") for (int m = 0; m < 4; ++m) _Pragma("unroll") for (int k = 0; k < 2; ++k) dst[m][k] = *(const PG8_LAS bf16x8*)(lds + PG8_SA(b, h) + aoff + m * 2048 + k * 1024); } while (0)
; #define PG8_MMA(ai, bj, At, Bt) do { __builtin_amdgcn_s_setprio(1); _Pragma("unroll") for (int m = 0; m < 4; ++m) _Pragma("unroll") for (int n = 0; n < 2; ++n) _Pragma("unroll") for (int k = 0; k < 2; ++k) \
;         acc[ai][bj][m][n] = __builtin_amdgcn_mfma_f32_16x16x32_bf16(Bt[n][k], At[m][k], acc[ai][bj][m][n], 0, 0, 0); __builtin_amdgcn_s_setprio(0); } while (0)
; #define PG8_WAIT_V(n) asm volatile("s_waitcnt vmcnt(" #n ")" ::: "memory")
; #define PG8_WAIT_L(n) asm volatile("s_waitcnt lgkmcnt(" #n ")" ::: "memory")
; #define PG8_BAR __builtin_amdgcn_s_barrier()
; #define PG8_SCHED __builtin_amdgcn_sched_barrier(0)
; template <class Epi, class Sched, bool ALIGN_EPI = false, bool SP2 = false>
; __device__ __forceinline__ void gemm_phase(PG8_LAS unsigned char* lds, const Gemm g, const Sched& S, const Epi& E) {
;     ...
;             PG8_LDA(At, 1, 1); PG8_STAGE(PG8_SB(1, 0), b3, voffB); PG8_STAGE(PG8_SB(1, 1), b3 + hstep, voffB); PG8_STAGE(PG8_SA(1, 0), a3, voffA);
;             PG8_WAIT_V(8); PG8_WAIT_L(0); PG8_BAR; PG8_MMA(1, 0, At, B0); PG8_MMA(1, 1, At, B1); PG8_BAR; PG8_SCHED;
;     __device__ __forceinline__ void operator()(const f32x4 (&acc)[2][2][4][2], const Unit& u, int wr, int wc, int fr, int fq) const {
;     ...
;             for (int m = 0; m < 4; ++m) { const int row = rbase + ai * 128 + m * 16; const f32x4* sp = (const f32x4*)(SSP + (size_t)row * 16);
;                 const f32x4 s4 = (sp[0] + sp[1]) + (sp[2] + sp[3]); const float rstd = __builtin_amdgcn_rsqf(((s4[0] + s4[1]) + (s4[2] + s4[3])) * (1.0f / 1024.0f) + EPS);
	s_add_i32 s36, s66, s39
	v_lshl_add_u64 v[216:217], v[216:217], 0, s[14:15]
	s_mov_b32 m0, s36
	ds_read_b128 v[184:187], v153 offset:49152
	ds_read_b128 v[188:191], v153 offset:50176
	ds_read_b128 v[192:195], v153 offset:51200
	ds_read_b128 v[196:199], v153 offset:52224
	ds_read_b128 v[200:203], v153 offset:53248
	ds_read_b128 v[204:207], v153 offset:54272
	ds_read_b128 v[208:211], v153 offset:55296
	ds_read_b128 v[212:215], v153 offset:56320
	global_load_lds_dwordx4 v[216:217], off
	s_add_i32 m0, s36, 0x2000
	s_add_u32 s34, s34, 0x40080
	v_lshl_add_u64 v[216:217], v[218:219], 0, s[14:15]
	s_addc_u32 s35, s35, 0
	s_add_i32 s36, s67, s39
	global_load_lds_dwordx4 v[216:217], off
	v_lshl_add_u64 v[216:217], s[34:35], 0, v[132:133]
	s_mov_b32 m0, s36
	s_nop 0
	global_load_lds_dwordx4 v[216:217], off
	v_lshl_add_u64 v[216:217], s[34:35], 0, v[128:129]
	s_add_i32 m0, s36, 0x2000
	s_nop 0
	global_load_lds_dwordx4 v[216:217], off
	v_lshl_add_u64 v[216:217], v[220:221], 0, s[14:15]
	s_mov_b32 m0, s49
	s_nop 0
	global_load_lds_dwordx4 v[216:217], off
	v_lshl_add_u64 v[216:217], v[222:223], 0, s[14:15]
	s_mov_b32 m0, s50
	s_nop 0
	global_load_lds_dwordx4 v[216:217], off
	s_waitcnt vmcnt(8)
	s_waitcnt lgkmcnt(0)
	s_barrier
	s_cmp_eq_u32 s65, 12
	s_cbranch_scc0 .Lessp_skip
	v_lshl_add_u32 v252, s28, 8, v148
	v_bfe_u32 v253, v226, 4, 2
	v_lshlrev_b32_e32 v252, 6, v252
	v_lshl_add_u32 v252, v253, 4, v252
	v_add_u32_e32 v253, 0x2000, v252
	global_load_dwordx4 v[228:231], v252, s[12:13]
	global_load_dwordx4 v[232:235], v252, s[12:13] offset:1024
	global_load_dwordx4 v[236:239], v252, s[12:13] offset:2048
	global_load_dwordx4 v[240:243], v252, s[12:13] offset:3072
	global_load_dwordx4 v[244:247], v253, s[12:13]
	global_load_dwordx4 v[248:251], v253, s[12:13] offset:1024
.Lessp_skip:
	s_setprio 1
	s_waitcnt lgkmcnt(0)
	v_mfma_f32_16x16x32_bf16 v[60:63], v[144:147], v[184:187], v[60:63]
	v_mfma_f32_16x16x32_bf16 v[56:59], v[160:163], v[184:187], v[56:59]
	v_mfma_f32_16x16x32_bf16 v[44:47], v[144:147], v[192:195], v[44:47]
	v_mfma_f32_16x16x32_bf16 v[40:43], v[160:163], v[192:195], v[40:43]
	v_mfma_f32_16x16x32_bf16 v[28:31], v[144:147], v[200:203], v[28:31]
	v_mfma_f32_16x16x32_bf16 v[24:27], v[160:163], v[200:203], v[24:27]
	v_mfma_f32_16x16x32_bf16 v[12:15], v[144:147], v[208:211], v[12:15]
	v_mfma_f32_16x16x32_bf16 v[8:11], v[160:163], v[208:211], v[8:11]
	v_mfma_f32_16x16x32_bf16 v[60:63], v[156:159], v[188:191], v[60:63]
	v_mfma_f32_16x16x32_bf16 v[56:59], v[164:167], v[188:191], v[56:59]
	v_mfma_f32_16x16x32_bf16 v[44:47], v[156:159], v[196:199], v[44:47]
	v_mfma_f32_16x16x32_bf16 v[40:43], v[164:167], v[196:199], v[40:43]
	v_mfma_f32_16x16x32_bf16 v[28:31], v[156:159], v[204:207], v[28:31]
	v_mfma_f32_16x16x32_bf16 v[24:27], v[164:167], v[204:207], v[24:27]
	v_mfma_f32_16x16x32_bf16 v[12:15], v[156:159], v[212:215], v[12:15]
	v_mfma_f32_16x16x32_bf16 v[8:11], v[164:167], v[212:215], v[8:11]
	s_setprio 0
	s_setprio 1
	v_mfma_f32_16x16x32_bf16 v[52:55], v[168:171], v[184:187], v[52:55]
	v_mfma_f32_16x16x32_bf16 v[48:51], v[176:179], v[184:187], v[48:51]
	v_mfma_f32_16x16x32_bf16 v[36:39], v[168:171], v[192:195], v[36:39]
	v_mfma_f32_16x16x32_bf16 v[32:35], v[176:179], v[192:195], v[32:35]
	v_mfma_f32_16x16x32_bf16 v[20:23], v[168:171], v[200:203], v[20:23]
	v_mfma_f32_16x16x32_bf16 v[16:19], v[176:179], v[200:203], v[16:19]
	v_mfma_f32_16x16x32_bf16 v[4:7], v[168:171], v[208:211], v[4:7]
	v_mfma_f32_16x16x32_bf16 v[0:3], v[176:179], v[208:211], v[0:3]
	v_mfma_f32_16x16x32_bf16 v[52:55], v[172:175], v[188:191], v[52:55]
	v_mfma_f32_16x16x32_bf16 v[48:51], v[180:183], v[188:191], v[48:51]
	v_mfma_f32_16x16x32_bf16 v[36:39], v[172:175], v[196:199], v[36:39]
	v_mfma_f32_16x16x32_bf16 v[32:35], v[180:183], v[196:199], v[32:35]
	v_mfma_f32_16x16x32_bf16 v[20:23], v[172:175], v[204:207], v[20:23]
	v_mfma_f32_16x16x32_bf16 v[16:19], v[180:183], v[204:207], v[16:19]
	v_mfma_f32_16x16x32_bf16 v[4:7], v[172:175], v[212:215], v[4:7]
	v_mfma_f32_16x16x32_bf16 v[0:3], v[180:183], v[212:215], v[0:3]
	s_setprio 0
	s_barrier
	s_mov_b32 s99, 0
	s_add_i32 s65, s65, 2
	s_add_u32 s30, s30, 0x100
	s_addc_u32 s31, s31, 0
	s_add_u32 s63, s63, 0x100
	s_addc_u32 s64, s64, 0
	s_cmp_gt_u32 s65, 13
	s_cbranch_scc0 .LBB0_1540
	v_lshl_add_u32 v146, s28, 8, v148
	v_ashrrev_i32_e32 v147, 31, v146
	v_lshlrev_b64 v[144:145], 6, v[146:147]
	v_lshl_add_u64 v[144:145], s[12:13], 0, v[144:145]
	v_bfe_u32 v156, v226, 4, 2
	v_lshlrev_b32_e32 v156, 4, v156
	v_mov_b32_e32 v157, 0
	v_lshl_add_u64 v[144:145], v[144:145], 0, v[156:157]
	s_mov_b64 s[98:99], 0x2000
	v_lshl_add_u64 v[222:223], v[144:145], 0, s[98:99]
	global_load_dwordx4 v[180:183], v[222:223], off offset:2048
	global_load_dwordx4 v[184:187], v[222:223], off offset:3072
	s_and_b64 vcc, exec, s[16:17]
	s_cbranch_vccz .LBB0_1543
	s_barrier
; __device__ __forceinline__ u32x4 pack8(const f32x4 a, const f32x4 b) { u32x4 w; w.x = cvt_pk_bf16(a[0], a[1]); w.y = cvt_pk_bf16(a[2], a[3]); w.z = cvt_pk_bf16(b[0], b[1]); w.w = cvt_pk_bf16(b[2], b[3]); return w; }
;     __device__ __forceinline__ void operator()(const f32x4 (&acc)[2][2][4][2], const Unit& u, int wr, int wc, int fr, int fq) const {
;     ...
;             for (int m = 0; m < 4; ++m) { const int row = rbase + ai * 128 + m * 16; const f32x4* sp = (const f32x4*)(SSP + (size_t)row * 16);
;                 const f32x4 s4 = (sp[0] + sp[1]) + (sp[2] + sp[3]); const float rstd = __builtin_amdgcn_rsqf(((s4[0] + s4[1]) + (s4[2] + s4[3])) * (1.0f / 1024.0f) + EPS);
; #pragma unroll
;                 for (int bj = 0; bj < 2; ++bj) { f32x4 v0 = acc[ai][bj][m][0] * rstd, v1 = acc[ai][bj][m][1] * rstd;
; #pragma unroll
;                     for (int i = 0; i < 4; ++i) { const float a = fmaxf(v0[i], 0.f), b = fmaxf(v1[i], 0.f); v0[i] = a * a; v1[i] = b * b; }
;                     *(u32x4*)(Z + (size_t)row * FF + cb + bj * 128) = pack8(v0, v1); }
.LBB0_1543:
	v_lshlrev_b64 v[220:221], 13, v[146:147]
	v_lshl_or_b32 v222, s60, 8, v150
	v_ashrrev_i32_e32 v223, 31, v222
	v_lshlrev_b64 v[222:223], 1, v[222:223]
	v_lshl_add_u64 v[220:221], s[8:9], 0, v[220:221]
	v_lshl_add_u64 v[220:221], v[220:221], 0, v[222:223]
	s_mov_b64 s[100:101], 0xa0000
	s_mov_b64 s[98:99], 0x20000
	s_waitcnt vmcnt(4)
	v_pk_add_f32 v[228:229], v[228:229], v[230:231]
	v_pk_add_f32 v[232:233], v[232:233], v[234:235]
	v_pk_add_f32 v[236:237], v[236:237], v[238:239]
	v_pk_add_f32 v[240:241], v[240:241], v[242:243]
	v_add_f32_e32 v228, v228, v229
	v_add_f32_e32 v232, v232, v233
	v_add_f32_e32 v236, v236, v237
	v_add_f32_e32 v240, v240, v241
	v_mov_b32_e32 v229, v228
	v_mov_b32_e32 v233, v232
	v_mov_b32_e32 v237, v236
	v_mov_b32_e32 v241, v240
	s_nop 1
	v_permlane16_swap_b32_e32 v229, v228
	v_permlane16_swap_b32_e32 v233, v232
	v_permlane16_swap_b32_e32 v237, v236
	v_permlane16_swap_b32_e32 v241, v240
	s_nop 1
	v_add_f32_e32 v228, v228, v229
	v_add_f32_e32 v232, v232, v233
	v_add_f32_e32 v236, v236, v237
	v_add_f32_e32 v240, v240, v241
	v_mov_b32_e32 v229, v228
	v_mov_b32_e32 v233, v232
	v_mov_b32_e32 v237, v236
	v_mov_b32_e32 v241, v240
	s_nop 1
	v_permlane32_swap_b32_e32 v229, v228
	v_permlane32_swap_b32_e32 v233, v232
	v_permlane32_swap_b32_e32 v237, v236
	v_permlane32_swap_b32_e32 v241, v240
	s_nop 1
	v_add_f32_e32 v228, v228, v229
	v_add_f32_e32 v232, v232, v233
	v_add_f32_e32 v236, v236, v237
	v_add_f32_e32 v240, v240, v241
	v_fmamk_f32 v228, v228, 0x3a800000, v154
	v_fmamk_f32 v232, v232, 0x3a800000, v154
	v_fmamk_f32 v236, v236, 0x3a800000, v154
	v_fmamk_f32 v240, v240, 0x3a800000, v154
	v_rsq_f32_e32 v228, v228
	v_rsq_f32_e32 v232, v232
	v_rsq_f32_e32 v236, v236
	v_rsq_f32_e32 v240, v240
	s_nop 0
	v_pk_mul_f32 v[112:113], v[112:113], v[228:229] op_sel_hi:[1,0]
	v_pk_mul_f32 v[114:115], v[114:115], v[228:229] op_sel_hi:[1,0]
	v_pk_mul_f32 v[116:117], v[116:117], v[228:229] op_sel_hi:[1,0]
	v_pk_mul_f32 v[118:119], v[118:119], v[228:229] op_sel_hi:[1,0]
	v_pk_mul_f32 v[120:121], v[120:121], v[228:229] op_sel_hi:[1,0]
	v_pk_mul_f32 v[122:123], v[122:123], v[228:229] op_sel_hi:[1,0]
	v_pk_mul_f32 v[124:125], v[124:125], v[228:229] op_sel_hi:[1,0]
	v_pk_mul_f32 v[126:127], v[126:127], v[228:229] op_sel_hi:[1,0]
	v_max_f32_e32 v112, 0, v112
	v_max_f32_e32 v113, 0, v113
	v_max_f32_e32 v114, 0, v114
	v_max_f32_e32 v115, 0, v115
	v_max_f32_e32 v116, 0, v116
	v_max_f32_e32 v117, 0, v117
	v_max_f32_e32 v118, 0, v118
	v_max_f32_e32 v119, 0, v119
	v_max_f32_e32 v120, 0, v120
	v_max_f32_e32 v121, 0, v121
	v_max_f32_e32 v122, 0, v122
	v_max_f32_e32 v123, 0, v123
	v_max_f32_e32 v124, 0, v124
	v_max_f32_e32 v125, 0, v125
	v_max_f32_e32 v126, 0, v126
	v_max_f32_e32 v127, 0, v127
	v_pk_mul_f32 v[112:113], v[112:113], v[112:113]
	v_pk_mul_f32 v[114:115], v[114:115], v[114:115]
	v_pk_mul_f32 v[116:117], v[116:117], v[116:117]
	v_pk_mul_f32 v[118:119], v[118:119], v[118:119]
	v_pk_mul_f32 v[120:121], v[120:121], v[120:121]
	v_pk_mul_f32 v[122:123], v[122:123], v[122:123]
	v_pk_mul_f32 v[124:125], v[124:125], v[124:125]
	v_pk_mul_f32 v[126:127], v[126:127], v[126:127]
	v_cvt_pk_bf16_f32 v124, v124, v125
	v_cvt_pk_bf16_f32 v125, v126, v127
	v_cvt_pk_bf16_f32 v126, v120, v121
	v_cvt_pk_bf16_f32 v127, v122, v123
	v_cvt_pk_bf16_f32 v116, v116, v117
	v_cvt_pk_bf16_f32 v117, v118, v119
	v_cvt_pk_bf16_f32 v118, v112, v113
	v_cvt_pk_bf16_f32 v119, v114, v115
	global_store_dwordx4 v[220:221], v[124:127], off
	global_store_dwordx4 v[220:221], v[116:119], off offset:256
	v_lshl_add_u64 v[220:221], v[220:221], 0, s[98:99]
	v_pk_mul_f32 v[96:97], v[96:97], v[232:233] op_sel_hi:[1,0]
	v_pk_mul_f32 v[98:99], v[98:99], v[232:233] op_sel_hi:[1,0]
	v_pk_mul_f32 v[100:101], v[100:101], v[232:233] op_sel_hi:[1,0]
	v_pk_mul_f32 v[102:103], v[102:103], v[232:233] op_sel_hi:[1,0]
	v_pk_mul_f32 v[104:105], v[104:105], v[232:233] op_sel_hi:[1,0]
	v_pk_mul_f32 v[106:107], v[106:107], v[232:233] op_sel_hi:[1,0]
	v_pk_mul_f32 v[108:109], v[108:109], v[232:233] op_sel_hi:[1,0]
	v_pk_mul_f32 v[110:111], v[110:111], v[232:233] op_sel_hi:[1,0]
	v_max_f32_e32 v96, 0, v96
	v_max_f32_e32 v97, 0, v97
	v_max_f32_e32 v98, 0, v98
	v_max_f32_e32 v99, 0, v99
	v_max_f32_e32 v100, 0, v100
	v_max_f32_e32 v101, 0, v101
	v_max_f32_e32 v102, 0, v102
	v_max_f32_e32 v103, 0, v103
	v_max_f32_e32 v104, 0, v104
	v_max_f32_e32 v105, 0, v105
	v_max_f32_e32 v106, 0, v106
	v_max_f32_e32 v107, 0, v107
	v_max_f32_e32 v108, 0, v108
	v_max_f32_e32 v109, 0, v109
	v_max_f32_e32 v110, 0, v110
	v_max_f32_e32 v111, 0, v111
	v_pk_mul_f32 v[96:97], v[96:97], v[96:97]
	v_pk_mul_f32 v[98:99], v[98:99], v[98:99]
	v_pk_mul_f32 v[100:101], v[100:101], v[100:101]
	v_pk_mul_f32 v[102:103], v[102:103], v[102:103]
	v_pk_mul_f32 v[104:105], v[104:105], v[104:105]
	v_pk_mul_f32 v[106:107], v[106:107], v[106:107]
	v_pk_mul_f32 v[108:109], v[108:109], v[108:109]
	v_pk_mul_f32 v[110:111], v[110:111], v[110:111]
	v_cvt_pk_bf16_f32 v108, v108, v109
	v_cvt_pk_bf16_f32 v109, v110, v111
	v_cvt_pk_bf16_f32 v110, v104, v105
	v_cvt_pk_bf16_f32 v111, v106, v107
	v_cvt_pk_bf16_f32 v100, v100, v101
	v_cvt_pk_bf16_f32 v101, v102, v103
	v_cvt_pk_bf16_f32 v102, v96, v97
	v_cvt_pk_bf16_f32 v103, v98, v99
	global_store_dwordx4 v[220:221], v[108:111], off
	global_store_dwordx4 v[220:221], v[100:103], off offset:256
	v_lshl_add_u64 v[220:221], v[220:221], 0, s[98:99]
	v_pk_mul_f32 v[80:81], v[80:81], v[236:237] op_sel_hi:[1,0]
	v_pk_mul_f32 v[82:83], v[82:83], v[236:237] op_sel_hi:[1,0]
	v_pk_mul_f32 v[84:85], v[84:85], v[236:237] op_sel_hi:[1,0]
	v_pk_mul_f32 v[86:87], v[86:87], v[236:237] op_sel_hi:[1,0]
; __device__ __forceinline__ u32x4 pack8(const f32x4 a, const f32x4 b) { u32x4 w; w.x = cvt_pk_bf16(a[0], a[1]); w.y = cvt_pk_bf16(a[2], a[3]); w.z = cvt_pk_bf16(b[0], b[1]); w.w = cvt_pk_bf16(b[2], b[3]); return w; }
;     __device__ __forceinline__ void operator()(const f32x4 (&acc)[2][2][4][2], const Unit& u, int wr, int wc, int fr, int fq) const {
;     ...
;             for (int m = 0; m < 4; ++m) { const int row = rbase + ai * 128 + m * 16; const f32x4* sp = (const f32x4*)(SSP + (size_t)row * 16);
;                 const f32x4 s4 = (sp[0] + sp[1]) + (sp[2] + sp[3]); const float rstd = __builtin_amdgcn_rsqf(((s4[0] + s4[1]) + (s4[2] + s4[3])) * (1.0f / 1024.0f) + EPS);
; #pragma unroll
;                 for (int bj = 0; bj < 2; ++bj) { f32x4 v0 = acc[ai][bj][m][0] * rstd, v1 = acc[ai][bj][m][1] * rstd;
; #pragma unroll
;                     for (int i = 0; i < 4; ++i) { const float a = fmaxf(v0[i], 0.f), b = fmaxf(v1[i], 0.f); v0[i] = a * a; v1[i] = b * b; }
;                     *(u32x4*)(Z + (size_t)row * FF + cb + bj * 128) = pack8(v0, v1); }
;                 asm volatile("" ::: "memory"); }
	v_pk_mul_f32 v[88:89], v[88:89], v[236:237] op_sel_hi:[1,0]
	v_pk_mul_f32 v[90:91], v[90:91], v[236:237] op_sel_hi:[1,0]
	v_pk_mul_f32 v[92:93], v[92:93], v[236:237] op_sel_hi:[1,0]
	v_pk_mul_f32 v[94:95], v[94:95], v[236:237] op_sel_hi:[1,0]
	v_max_f32_e32 v80, 0, v80
	v_max_f32_e32 v81, 0, v81
	v_max_f32_e32 v82, 0, v82
	v_max_f32_e32 v83, 0, v83
	v_max_f32_e32 v84, 0, v84
	v_max_f32_e32 v85, 0, v85
	v_max_f32_e32 v86, 0, v86
	v_max_f32_e32 v87, 0, v87
	v_max_f32_e32 v88, 0, v88
	v_max_f32_e32 v89, 0, v89
	v_max_f32_e32 v90, 0, v90
	v_max_f32_e32 v91, 0, v91
	v_max_f32_e32 v92, 0, v92
	v_max_f32_e32 v93, 0, v93
	v_max_f32_e32 v94, 0, v94
	v_max_f32_e32 v95, 0, v95
	v_pk_mul_f32 v[80:81], v[80:81], v[80:81]
	v_pk_mul_f32 v[82:83], v[82:83], v[82:83]
	v_pk_mul_f32 v[84:85], v[84:85], v[84:85]
	v_pk_mul_f32 v[86:87], v[86:87], v[86:87]
	v_pk_mul_f32 v[88:89], v[88:89], v[88:89]
	v_pk_mul_f32 v[90:91], v[90:91], v[90:91]
	v_pk_mul_f32 v[92:93], v[92:93], v[92:93]
	v_pk_mul_f32 v[94:95], v[94:95], v[94:95]
	v_cvt_pk_bf16_f32 v92, v92, v93
	v_cvt_pk_bf16_f32 v93, v94, v95
	v_cvt_pk_bf16_f32 v94, v88, v89
	v_cvt_pk_bf16_f32 v95, v90, v91
	v_cvt_pk_bf16_f32 v84, v84, v85
	v_cvt_pk_bf16_f32 v85, v86, v87
	v_cvt_pk_bf16_f32 v86, v80, v81
	v_cvt_pk_bf16_f32 v87, v82, v83
	global_store_dwordx4 v[220:221], v[92:95], off
	global_store_dwordx4 v[220:221], v[84:87], off offset:256
	v_lshl_add_u64 v[220:221], v[220:221], 0, s[98:99]
	v_pk_mul_f32 v[64:65], v[64:65], v[240:241] op_sel_hi:[1,0]
	v_pk_mul_f32 v[66:67], v[66:67], v[240:241] op_sel_hi:[1,0]
	v_pk_mul_f32 v[68:69], v[68:69], v[240:241] op_sel_hi:[1,0]
	v_pk_mul_f32 v[70:71], v[70:71], v[240:241] op_sel_hi:[1,0]
	v_pk_mul_f32 v[72:73], v[72:73], v[240:241] op_sel_hi:[1,0]
	v_pk_mul_f32 v[74:75], v[74:75], v[240:241] op_sel_hi:[1,0]
	v_pk_mul_f32 v[76:77], v[76:77], v[240:241] op_sel_hi:[1,0]
	v_pk_mul_f32 v[78:79], v[78:79], v[240:241] op_sel_hi:[1,0]
	v_max_f32_e32 v64, 0, v64
	v_max_f32_e32 v65, 0, v65
	v_max_f32_e32 v66, 0, v66
	v_max_f32_e32 v67, 0, v67
	v_max_f32_e32 v68, 0, v68
	v_max_f32_e32 v69, 0, v69
	v_max_f32_e32 v70, 0, v70
	v_max_f32_e32 v71, 0, v71
	v_max_f32_e32 v72, 0, v72
	v_max_f32_e32 v73, 0, v73
	v_max_f32_e32 v74, 0, v74
	v_max_f32_e32 v75, 0, v75
	v_max_f32_e32 v76, 0, v76
	v_max_f32_e32 v77, 0, v77
	v_max_f32_e32 v78, 0, v78
	v_max_f32_e32 v79, 0, v79
	v_pk_mul_f32 v[64:65], v[64:65], v[64:65]
	v_pk_mul_f32 v[66:67], v[66:67], v[66:67]
	v_pk_mul_f32 v[68:69], v[68:69], v[68:69]
	v_pk_mul_f32 v[70:71], v[70:71], v[70:71]
	v_pk_mul_f32 v[72:73], v[72:73], v[72:73]
	v_pk_mul_f32 v[74:75], v[74:75], v[74:75]
	v_pk_mul_f32 v[76:77], v[76:77], v[76:77]
	v_pk_mul_f32 v[78:79], v[78:79], v[78:79]
	v_cvt_pk_bf16_f32 v76, v76, v77
	v_cvt_pk_bf16_f32 v77, v78, v79
	v_cvt_pk_bf16_f32 v78, v72, v73
	v_cvt_pk_bf16_f32 v79, v74, v75
	v_cvt_pk_bf16_f32 v68, v68, v69
	v_cvt_pk_bf16_f32 v69, v70, v71
	v_cvt_pk_bf16_f32 v70, v64, v65
	v_cvt_pk_bf16_f32 v71, v66, v67
	global_store_dwordx4 v[220:221], v[76:79], off
	global_store_dwordx4 v[220:221], v[68:71], off offset:256
	v_lshl_add_u64 v[220:221], v[220:221], 0, s[100:101]
	s_waitcnt vmcnt(8)
	v_pk_add_f32 v[244:245], v[244:245], v[246:247]
	v_pk_add_f32 v[248:249], v[248:249], v[250:251]
	v_pk_add_f32 v[180:181], v[180:181], v[182:183]
	v_pk_add_f32 v[184:185], v[184:185], v[186:187]
	v_add_f32_e32 v244, v244, v245
	v_add_f32_e32 v248, v248, v249
	v_add_f32_e32 v180, v180, v181
	v_add_f32_e32 v184, v184, v185
	v_mov_b32_e32 v245, v244
	v_mov_b32_e32 v249, v248
	v_mov_b32_e32 v181, v180
	v_mov_b32_e32 v185, v184
	s_nop 1
	v_permlane16_swap_b32_e32 v245, v244
	v_permlane16_swap_b32_e32 v249, v248
	v_permlane16_swap_b32_e32 v181, v180
	v_permlane16_swap_b32_e32 v185, v184
	s_nop 1
	v_add_f32_e32 v244, v244, v245
	v_add_f32_e32 v248, v248, v249
	v_add_f32_e32 v180, v180, v181
	v_add_f32_e32 v184, v184, v185
	v_mov_b32_e32 v245, v244
	v_mov_b32_e32 v249, v248
	v_mov_b32_e32 v181, v180
	v_mov_b32_e32 v185, v184
	s_nop 1
	v_permlane32_swap_b32_e32 v245, v244
	v_permlane32_swap_b32_e32 v249, v248
	v_permlane32_swap_b32_e32 v181, v180
	v_permlane32_swap_b32_e32 v185, v184
	s_nop 1
	v_add_f32_e32 v244, v244, v245
	v_add_f32_e32 v248, v248, v249
	v_add_f32_e32 v180, v180, v181
	v_add_f32_e32 v184, v184, v185
	v_fmamk_f32 v244, v244, 0x3a800000, v154
	v_fmamk_f32 v248, v248, 0x3a800000, v154
	v_fmamk_f32 v180, v180, 0x3a800000, v154
	v_fmamk_f32 v184, v184, 0x3a800000, v154
	v_rsq_f32_e32 v244, v244
	v_rsq_f32_e32 v248, v248
	v_rsq_f32_e32 v180, v180
	v_rsq_f32_e32 v184, v184
	s_nop 0
	v_pk_mul_f32 v[48:49], v[48:49], v[244:245] op_sel_hi:[1,0]
	v_pk_mul_f32 v[50:51], v[50:51], v[244:245] op_sel_hi:[1,0]
	v_pk_mul_f32 v[52:53], v[52:53], v[244:245] op_sel_hi:[1,0]
	v_pk_mul_f32 v[54:55], v[54:55], v[244:245] op_sel_hi:[1,0]
	v_pk_mul_f32 v[56:57], v[56:57], v[244:245] op_sel_hi:[1,0]
	v_pk_mul_f32 v[58:59], v[58:59], v[244:245] op_sel_hi:[1,0]
	v_pk_mul_f32 v[60:61], v[60:61], v[244:245] op_sel_hi:[1,0]
	v_pk_mul_f32 v[62:63], v[62:63], v[244:245] op_sel_hi:[1,0]
	v_max_f32_e32 v48, 0, v48
	v_max_f32_e32 v49, 0, v49
	v_max_f32_e32 v50, 0, v50
	v_max_f32_e32 v51, 0, v51
	v_max_f32_e32 v52, 0, v52
	v_max_f32_e32 v53, 0, v53
	v_max_f32_e32 v54, 0, v54
	v_max_f32_e32 v55, 0, v55
	v_max_f32_e32 v56, 0, v56
	v_max_f32_e32 v57, 0, v57
	v_max_f32_e32 v58, 0, v58
	v_max_f32_e32 v59, 0, v59
	v_max_f32_e32 v60, 0, v60
	v_max_f32_e32 v61, 0, v61
	v_max_f32_e32 v62, 0, v62
	v_max_f32_e32 v63, 0, v63
	v_pk_mul_f32 v[48:49], v[48:49], v[48:49]
	v_pk_mul_f32 v[50:51], v[50:51], v[50:51]
	v_pk_mul_f32 v[52:53], v[52:53], v[52:53]
	v_pk_mul_f32 v[54:55], v[54:55], v[54:55]
; __device__ __forceinline__ u32x4 pack8(const f32x4 a, const f32x4 b) { u32x4 w; w.x = cvt_pk_bf16(a[0], a[1]); w.y = cvt_pk_bf16(a[2], a[3]); w.z = cvt_pk_bf16(b[0], b[1]); w.w = cvt_pk_bf16(b[2], b[3]); return w; }
;     __device__ __forceinline__ void operator()(const f32x4 (&acc)[2][2][4][2], const Unit& u, int wr, int wc, int fr, int fq) const {
;     ...
;             for (int m = 0; m < 4; ++m) { const int row = rbase + ai * 128 + m * 16; const f32x4* sp = (const f32x4*)(SSP + (size_t)row * 16);
;                 const f32x4 s4 = (sp[0] + sp[1]) + (sp[2] + sp[3]); const float rstd = __builtin_amdgcn_rsqf(((s4[0] + s4[1]) + (s4[2] + s4[3])) * (1.0f / 1024.0f) + EPS);
; #pragma unroll
;                 for (int bj = 0; bj < 2; ++bj) { f32x4 v0 = acc[ai][bj][m][0] * rstd, v1 = acc[ai][bj][m][1] * rstd;
; #pragma unroll
;                     for (int i = 0; i < 4; ++i) { const float a = fmaxf(v0[i], 0.f), b = fmaxf(v1[i], 0.f); v0[i] = a * a; v1[i] = b * b; }
;                     *(u32x4*)(Z + (size_t)row * FF + cb + bj * 128) = pack8(v0, v1); }
;                 asm volatile("" ::: "memory"); }
	v_pk_mul_f32 v[56:57], v[56:57], v[56:57]
	v_pk_mul_f32 v[58:59], v[58:59], v[58:59]
	v_pk_mul_f32 v[60:61], v[60:61], v[60:61]
	v_pk_mul_f32 v[62:63], v[62:63], v[62:63]
	v_cvt_pk_bf16_f32 v60, v60, v61
	v_cvt_pk_bf16_f32 v61, v62, v63
	v_cvt_pk_bf16_f32 v62, v56, v57
	v_cvt_pk_bf16_f32 v63, v58, v59
	v_cvt_pk_bf16_f32 v52, v52, v53
	v_cvt_pk_bf16_f32 v53, v54, v55
	v_cvt_pk_bf16_f32 v54, v48, v49
	v_cvt_pk_bf16_f32 v55, v50, v51
	global_store_dwordx4 v[220:221], v[60:63], off
	global_store_dwordx4 v[220:221], v[52:55], off offset:256
	v_lshl_add_u64 v[220:221], v[220:221], 0, s[98:99]
	v_pk_mul_f32 v[32:33], v[32:33], v[248:249] op_sel_hi:[1,0]
	v_pk_mul_f32 v[34:35], v[34:35], v[248:249] op_sel_hi:[1,0]
	v_pk_mul_f32 v[36:37], v[36:37], v[248:249] op_sel_hi:[1,0]
	v_pk_mul_f32 v[38:39], v[38:39], v[248:249] op_sel_hi:[1,0]
	v_pk_mul_f32 v[40:41], v[40:41], v[248:249] op_sel_hi:[1,0]
	v_pk_mul_f32 v[42:43], v[42:43], v[248:249] op_sel_hi:[1,0]
	v_pk_mul_f32 v[44:45], v[44:45], v[248:249] op_sel_hi:[1,0]
	v_pk_mul_f32 v[46:47], v[46:47], v[248:249] op_sel_hi:[1,0]
	v_max_f32_e32 v32, 0, v32
	v_max_f32_e32 v33, 0, v33
	v_max_f32_e32 v34, 0, v34
	v_max_f32_e32 v35, 0, v35
	v_max_f32_e32 v36, 0, v36
	v_max_f32_e32 v37, 0, v37
	v_max_f32_e32 v38, 0, v38
	v_max_f32_e32 v39, 0, v39
	v_max_f32_e32 v40, 0, v40
	v_max_f32_e32 v41, 0, v41
	v_max_f32_e32 v42, 0, v42
	v_max_f32_e32 v43, 0, v43
	v_max_f32_e32 v44, 0, v44
	v_max_f32_e32 v45, 0, v45
	v_max_f32_e32 v46, 0, v46
	v_max_f32_e32 v47, 0, v47
	v_pk_mul_f32 v[32:33], v[32:33], v[32:33]
	v_pk_mul_f32 v[34:35], v[34:35], v[34:35]
	v_pk_mul_f32 v[36:37], v[36:37], v[36:37]
	v_pk_mul_f32 v[38:39], v[38:39], v[38:39]
	v_pk_mul_f32 v[40:41], v[40:41], v[40:41]
	v_pk_mul_f32 v[42:43], v[42:43], v[42:43]
	v_pk_mul_f32 v[44:45], v[44:45], v[44:45]
	v_pk_mul_f32 v[46:47], v[46:47], v[46:47]
	v_cvt_pk_bf16_f32 v44, v44, v45
	v_cvt_pk_bf16_f32 v45, v46, v47
	v_cvt_pk_bf16_f32 v46, v40, v41
	v_cvt_pk_bf16_f32 v47, v42, v43
	v_cvt_pk_bf16_f32 v36, v36, v37
	v_cvt_pk_bf16_f32 v37, v38, v39
	v_cvt_pk_bf16_f32 v38, v32, v33
	v_cvt_pk_bf16_f32 v39, v34, v35
	global_store_dwordx4 v[220:221], v[44:47], off
	global_store_dwordx4 v[220:221], v[36:39], off offset:256
	v_lshl_add_u64 v[220:221], v[220:221], 0, s[98:99]
	v_pk_mul_f32 v[16:17], v[16:17], v[180:181] op_sel_hi:[1,0]
	v_pk_mul_f32 v[18:19], v[18:19], v[180:181] op_sel_hi:[1,0]
	v_pk_mul_f32 v[20:21], v[20:21], v[180:181] op_sel_hi:[1,0]
	v_pk_mul_f32 v[22:23], v[22:23], v[180:181] op_sel_hi:[1,0]
	v_pk_mul_f32 v[24:25], v[24:25], v[180:181] op_sel_hi:[1,0]
	v_pk_mul_f32 v[26:27], v[26:27], v[180:181] op_sel_hi:[1,0]
	v_pk_mul_f32 v[28:29], v[28:29], v[180:181] op_sel_hi:[1,0]
	v_pk_mul_f32 v[30:31], v[30:31], v[180:181] op_sel_hi:[1,0]
	v_max_f32_e32 v16, 0, v16
	v_max_f32_e32 v17, 0, v17
	v_max_f32_e32 v18, 0, v18
	v_max_f32_e32 v19, 0, v19
	v_max_f32_e32 v20, 0, v20
	v_max_f32_e32 v21, 0, v21
	v_max_f32_e32 v22, 0, v22
	v_max_f32_e32 v23, 0, v23
	v_max_f32_e32 v24, 0, v24
	v_max_f32_e32 v25, 0, v25
	v_max_f32_e32 v26, 0, v26
	v_max_f32_e32 v27, 0, v27
	v_max_f32_e32 v28, 0, v28
	v_max_f32_e32 v29, 0, v29
	v_max_f32_e32 v30, 0, v30
	v_max_f32_e32 v31, 0, v31
	v_pk_mul_f32 v[16:17], v[16:17], v[16:17]
	v_pk_mul_f32 v[18:19], v[18:19], v[18:19]
	v_pk_mul_f32 v[20:21], v[20:21], v[20:21]
	v_pk_mul_f32 v[22:23], v[22:23], v[22:23]
	v_pk_mul_f32 v[24:25], v[24:25], v[24:25]
	v_pk_mul_f32 v[26:27], v[26:27], v[26:27]
	v_pk_mul_f32 v[28:29], v[28:29], v[28:29]
	v_pk_mul_f32 v[30:31], v[30:31], v[30:31]
	v_cvt_pk_bf16_f32 v28, v28, v29
	v_cvt_pk_bf16_f32 v29, v30, v31
	v_cvt_pk_bf16_f32 v30, v24, v25
	v_cvt_pk_bf16_f32 v31, v26, v27
	v_cvt_pk_bf16_f32 v20, v20, v21
	v_cvt_pk_bf16_f32 v21, v22, v23
	v_cvt_pk_bf16_f32 v22, v16, v17
	v_cvt_pk_bf16_f32 v23, v18, v19
	global_store_dwordx4 v[220:221], v[28:31], off
	global_store_dwordx4 v[220:221], v[20:23], off offset:256
	v_lshl_add_u64 v[220:221], v[220:221], 0, s[98:99]
	v_pk_mul_f32 v[0:1], v[0:1], v[184:185] op_sel_hi:[1,0]
	v_pk_mul_f32 v[2:3], v[2:3], v[184:185] op_sel_hi:[1,0]
	v_pk_mul_f32 v[4:5], v[4:5], v[184:185] op_sel_hi:[1,0]
	v_pk_mul_f32 v[6:7], v[6:7], v[184:185] op_sel_hi:[1,0]
	v_pk_mul_f32 v[8:9], v[8:9], v[184:185] op_sel_hi:[1,0]
	v_pk_mul_f32 v[10:11], v[10:11], v[184:185] op_sel_hi:[1,0]
	v_pk_mul_f32 v[12:13], v[12:13], v[184:185] op_sel_hi:[1,0]
	v_pk_mul_f32 v[14:15], v[14:15], v[184:185] op_sel_hi:[1,0]
	v_max_f32_e32 v0, 0, v0
	v_max_f32_e32 v1, 0, v1
	v_max_f32_e32 v2, 0, v2
	v_max_f32_e32 v3, 0, v3
	v_max_f32_e32 v4, 0, v4
	v_max_f32_e32 v5, 0, v5
	v_max_f32_e32 v6, 0, v6
	v_max_f32_e32 v7, 0, v7
	v_max_f32_e32 v8, 0, v8
	v_max_f32_e32 v9, 0, v9
	v_max_f32_e32 v10, 0, v10
	v_max_f32_e32 v11, 0, v11
	v_max_f32_e32 v12, 0, v12
	v_max_f32_e32 v13, 0, v13
	v_max_f32_e32 v14, 0, v14
	v_max_f32_e32 v15, 0, v15
	v_pk_mul_f32 v[0:1], v[0:1], v[0:1]
	v_pk_mul_f32 v[2:3], v[2:3], v[2:3]
	v_pk_mul_f32 v[4:5], v[4:5], v[4:5]
	v_pk_mul_f32 v[6:7], v[6:7], v[6:7]
	v_pk_mul_f32 v[8:9], v[8:9], v[8:9]
	v_pk_mul_f32 v[10:11], v[10:11], v[10:11]
	v_pk_mul_f32 v[12:13], v[12:13], v[12:13]
	v_pk_mul_f32 v[14:15], v[14:15], v[14:15]
	v_cvt_pk_bf16_f32 v12, v12, v13
	v_cvt_pk_bf16_f32 v13, v14, v15
	v_cvt_pk_bf16_f32 v14, v8, v9
	v_cvt_pk_bf16_f32 v15, v10, v11
	v_cvt_pk_bf16_f32 v4, v4, v5
	v_cvt_pk_bf16_f32 v5, v6, v7
	v_cvt_pk_bf16_f32 v6, v0, v1
	v_cvt_pk_bf16_f32 v7, v2, v3
	global_store_dwordx4 v[220:221], v[12:15], off
	global_store_dwordx4 v[220:221], v[4:7], off offset:256
	s_andn2_b64 vcc, exec, s[4:5]
	s_mov_b64 s[4:5], -1
	s_cbranch_vccnz .LBB0_1536
	s_andn2_b64 vcc, exec, s[6:7]
	s_cbranch_vccnz .LBB0_1535
	s_barrier
	s_branch .LBB0_1535
